# v10 + static split of phase-1 weight conversion: the 192 GEMM workgroups convert ffn_w_up L1 and cd_w_out after their last tile, converter workgroups do the rest
# speedup vs baseline: 1.0012x; 1.0012x over previous
; #define TR_JOB_GU(W_, WT_, off_, gain_) { constexpr int nnb_ = DFF / 32, nit_ = (DM / 64) * nnb_; \
;     if (r < nit_) { const int kb_ = r / nnb_, nb_ = r % nnb_, c0_ = 32 * nb_; \
;         return TrDesc{(W_) + (size_t)(64 * kb_) * DFF + c0_, (WT_) + (size_t)(256 * (c0_ / 128) + (c0_ % 128) + (off_)) * DM + 64 * kb_, (gain_) + 64 * kb_, DFF, DM}; } r -= nit_; }
; __device__ __forceinline__ TrDesc p0_item(const Params& p, int it) {
;     unsigned char* ws = p.ws;
;     bf16_t* WAB_IN = (bf16_t*)(ws + WS_WAB_IN); bf16_t* WAB_OUT = (bf16_t*)(ws + WS_WAB_OUT); bf16_t* WGU0 = (bf16_t*)(ws + WS_WGU0); bf16_t* WDN0 = (bf16_t*)(ws + WS_WDN0);
;     bf16_t* WCD_IN = (bf16_t*)(ws + WS_WCD_IN); bf16_t* WGU1 = (bf16_t*)(ws + WS_WGU1);
;     bf16_t* WRG = (bf16_t*)(ws + WS_WRG);
;     int r = it;
;     TR_JOB(p.ab_w_in, AB_IN, DM, 0, 6144, WAB_IN, 0, p.norm_mix)
;     TR_JOB(p.ab_w_in, AB_IN, DM, 6160, 6144, WAB_IN, 6144, p.norm_mix)
;     TR_JOB(p.ab_w_out, DM, DM, 0, DM, WAB_OUT, 0, (const float*)nullptr)
;     TR_JOB_GU(p.ffn_w_gate, WGU0, 0, p.norm_ffn)
;     TR_JOB_GU(p.ffn_w_up, WGU0, 128, p.norm_ffn)
;     TR_JOB(p.ffn_w_down, DM, DFF, 0, DM, WDN0, 0, (const float*)nullptr)
;     TR_JOB(p.cd_w_in, CD_IN, DM, 0, CD_IN, WCD_IN, 0, p.norm_mix + DM)
;     TR_JOB_GU(p.ffn_w_gate + (size_t)DM * DFF, WGU1, 0, p.norm_ffn + DM)
;     TR_JOB_GU(p.ffn_w_up + (size_t)DM * DFF, WGU1, 128, p.norm_ffn + DM)
;     TR_JOB(p.cd_w_out, DM, DM, 0, DM, (bf16_t*)(ws + WS_WCD_OUT), 0, (const float*)nullptr)
;     const int mat = r / 32, rr = r % 32, kb_ = rr / 8, nb_ = rr % 8;
;     const float* W = (mat < 8 ? p.rg_w_x : p.rg_w_a) + (size_t)(mat & 7) * 65536;
;     return TrDesc{W + (size_t)(64 * kb_) * 256 + 32 * nb_, WRG + (size_t)mat * 65536 + (size_t)(32 * nb_) * 256 + 64 * kb_, nullptr, 256, 256};
; }
.Lcv_job_abo:
	s_load_dwordx2 s[60:61], s[24:25], 0x58
	s_load_dwordx2 s[62:63], s[24:25], 0xb8
	s_mov_b32 s6, 0x4000
	s_mov_b32 s7, 0x2000
	s_mov_b32 s75, 0
	s_and_b32 s9, s18, 63
	s_lshr_b32 s10, s18, 6
	s_add_i32 s10, s10, 5
	s_and_b32 s10, s10, 7
	s_sub_i32 s74, 31, s10
	s_lshr_b32 s74, s74, 3
	s_add_i32 s74, s74, 1
	s_lshl_b32 s11, s9, 6
	s_mul_i32 s11, s11, s6
	s_lshl_b32 s21, s10, 9
	s_add_u32 s11, s11, s21
	s_mul_i32 s23, s10, 128
	s_mul_i32 s23, s23, s7
	s_lshl_b32 s26, s9, 7
	s_add_u32 s23, s23, s26
	s_mov_b32 s70, 0x1000
	s_mov_b32 s71, 0
	s_mov_b32 s72, 0x800000
	s_mov_b32 s73, 0
	s_waitcnt lgkmcnt(0)
	s_add_u32 s60, s60, s11
	s_addc_u32 s61, s61, 0
	s_add_u32 s62, s62, 0x6100000
	s_addc_u32 s63, s63, 0
	s_add_u32 s62, s62, s23
	s_addc_u32 s63, s63, 0
	s_lshl_b32 s26, s7, 5
	s_add_u32 s64, s62, s26
	s_addc_u32 s65, s63, 0
	s_add_u32 s66, s64, s26
	s_addc_u32 s67, s65, 0
	s_add_u32 s68, s66, s26
	s_addc_u32 s69, s67, 0
	s_mov_b32 s8, 0
	s_branch .Lcv_run
.Lcv_back_0:
.Lcv_job_g0:
	s_load_dwordx2 s[60:61], s[24:25], 0x18
	s_load_dwordx2 s[62:63], s[24:25], 0xb8
	s_load_dwordx2 s[4:5], s[24:25], 0x10
	s_mov_b32 s6, 0xac00
	s_mov_b32 s7, 0x2000
	s_mov_b32 s75, 1
	s_and_b32 s9, s18, 63
	s_lshr_b32 s10, s18, 6
	s_add_i32 s10, s10, 6
	s_and_b32 s10, s10, 7
	s_sub_i32 s74, 85, s10
	s_lshr_b32 s74, s74, 3
	s_add_i32 s74, s74, 1
	s_lshl_b32 s11, s9, 6
	s_mul_i32 s11, s11, s6
	s_lshl_b32 s21, s10, 9
	s_add_u32 s11, s11, s21
	s_mul_i32 s23, s10, 256
	s_mul_i32 s23, s23, s7
	s_lshl_b32 s26, s9, 7
	s_add_u32 s23, s23, s26
	s_mov_b32 s70, 0x1000
	s_mov_b32 s71, 0
	s_mov_b32 s72, 0x1000000
	s_mov_b32 s73, 0
	s_waitcnt lgkmcnt(0)
	s_add_u32 s60, s60, s11
	s_addc_u32 s61, s61, 0
	s_add_u32 s62, s62, 0x8100000
	s_addc_u32 s63, s63, 0
	s_add_u32 s62, s62, s23
	s_addc_u32 s63, s63, 0
	s_lshl_b32 s26, s7, 5
	s_add_u32 s64, s62, s26
	s_addc_u32 s65, s63, 0
	s_add_u32 s66, s64, s26
	s_addc_u32 s67, s65, 0
	s_add_u32 s68, s66, s26
	s_addc_u32 s69, s67, 0
	s_lshl_b32 s26, s9, 8
	s_add_u32 s4, s4, s26
	s_addc_u32 s5, s5, 0
	s_mov_b32 s8, 1
	s_branch .Lcv_run
.Lcv_back_1:
.Lcv_job_u0:
	s_load_dwordx2 s[60:61], s[24:25], 0x20
	s_load_dwordx2 s[62:63], s[24:25], 0xb8
	s_load_dwordx2 s[4:5], s[24:25], 0x10
	s_mov_b32 s6, 0xac00
	s_mov_b32 s7, 0x2000
	s_mov_b32 s75, 2
	s_and_b32 s9, s18, 63
	s_lshr_b32 s10, s18, 6
	s_add_i32 s10, s10, 0
	s_and_b32 s10, s10, 7
	s_sub_i32 s74, 85, s10
	s_lshr_b32 s74, s74, 3
	s_add_i32 s74, s74, 1
	s_lshl_b32 s11, s9, 6
	s_mul_i32 s11, s11, s6
	s_lshl_b32 s21, s10, 9
	s_add_u32 s11, s11, s21
	s_mul_i32 s23, s10, 256
	s_add_i32 s23, s23, 128
	s_mul_i32 s23, s23, s7
	s_lshl_b32 s26, s9, 7
	s_add_u32 s23, s23, s26
	s_mov_b32 s70, 0x1000
	s_mov_b32 s71, 0
	s_mov_b32 s72, 0x1000000
	s_mov_b32 s73, 0
	s_waitcnt lgkmcnt(0)
	s_add_u32 s60, s60, s11
	s_addc_u32 s61, s61, 0
	s_add_u32 s62, s62, 0x8100000
	s_addc_u32 s63, s63, 0
	s_add_u32 s62, s62, s23
	s_addc_u32 s63, s63, 0
	s_lshl_b32 s26, s7, 5
	s_add_u32 s64, s62, s26
	s_addc_u32 s65, s63, 0
	s_add_u32 s66, s64, s26
	s_addc_u32 s67, s65, 0
	s_add_u32 s68, s66, s26
	s_addc_u32 s69, s67, 0
	s_lshl_b32 s26, s9, 8
	s_add_u32 s4, s4, s26
	s_addc_u32 s5, s5, 0
	s_mov_b32 s8, 1
	s_branch .Lcv_run
.Lcv_back_2:
.Lcv_job_dn0:
	s_load_dwordx2 s[60:61], s[24:25], 0x28
	s_load_dwordx2 s[62:63], s[24:25], 0xb8
	s_mov_b32 s6, 0x4000
	s_mov_b32 s7, 0x5600
	s_mov_b32 s75, 3
	s_and_b32 s10, s18, 31
	s_lshr_b32 s9, s18, 5
	s_add_i32 s9, s9, 1
	s_and_b32 s9, s9, 15
	s_sub_i32 s74, 171, s9
	s_lshr_b32 s74, s74, 4
	s_add_i32 s74, s74, 1
	s_lshl_b32 s11, s9, 6
	s_mul_i32 s11, s11, s6
	s_lshl_b32 s21, s10, 9
	s_add_u32 s11, s11, s21
	s_lshl_b32 s23, s10, 7
	s_mul_i32 s23, s23, s7
	s_lshl_b32 s26, s9, 7
	s_add_u32 s23, s23, s26
	s_mov_b32 s70, 0x1000000
	s_mov_b32 s71, 0
	s_mov_b32 s72, 0x800
	s_mov_b32 s73, 0
	s_waitcnt lgkmcnt(0)
	s_add_u32 s60, s60, s11
	s_addc_u32 s61, s61, 0
	s_add_u32 s62, s62, 0x12d00000
	s_addc_u32 s63, s63, 0
	s_add_u32 s62, s62, s23
	s_addc_u32 s63, s63, 0
	s_lshl_b32 s26, s7, 5
	s_add_u32 s64, s62, s26
	s_addc_u32 s65, s63, 0
	s_add_u32 s66, s64, s26
	s_addc_u32 s67, s65, 0
	s_add_u32 s68, s66, s26
	s_addc_u32 s69, s67, 0
	s_mov_b32 s8, 0
	s_branch .Lcv_run
; #define TR_JOB_GU(W_, WT_, off_, gain_) { constexpr int nnb_ = DFF / 32, nit_ = (DM / 64) * nnb_; \
;     if (r < nit_) { const int kb_ = r / nnb_, nb_ = r % nnb_, c0_ = 32 * nb_; \
;         return TrDesc{(W_) + (size_t)(64 * kb_) * DFF + c0_, (WT_) + (size_t)(256 * (c0_ / 128) + (c0_ % 128) + (off_)) * DM + 64 * kb_, (gain_) + 64 * kb_, DFF, DM}; } r -= nit_; }
; __device__ __forceinline__ TrDesc p0_item(const Params& p, int it) {
;     unsigned char* ws = p.ws;
;     bf16_t* WAB_IN = (bf16_t*)(ws + WS_WAB_IN); bf16_t* WAB_OUT = (bf16_t*)(ws + WS_WAB_OUT); bf16_t* WGU0 = (bf16_t*)(ws + WS_WGU0); bf16_t* WDN0 = (bf16_t*)(ws + WS_WDN0);
;     bf16_t* WCD_IN = (bf16_t*)(ws + WS_WCD_IN); bf16_t* WGU1 = (bf16_t*)(ws + WS_WGU1);
;     bf16_t* WRG = (bf16_t*)(ws + WS_WRG);
;     int r = it;
;     TR_JOB(p.ab_w_in, AB_IN, DM, 0, 6144, WAB_IN, 0, p.norm_mix)
;     TR_JOB(p.ab_w_in, AB_IN, DM, 6160, 6144, WAB_IN, 6144, p.norm_mix)
;     TR_JOB(p.ab_w_out, DM, DM, 0, DM, WAB_OUT, 0, (const float*)nullptr)
;     TR_JOB_GU(p.ffn_w_gate, WGU0, 0, p.norm_ffn)
;     TR_JOB_GU(p.ffn_w_up, WGU0, 128, p.norm_ffn)
;     TR_JOB(p.ffn_w_down, DM, DFF, 0, DM, WDN0, 0, (const float*)nullptr)
;     TR_JOB(p.cd_w_in, CD_IN, DM, 0, CD_IN, WCD_IN, 0, p.norm_mix + DM)
;     TR_JOB_GU(p.ffn_w_gate + (size_t)DM * DFF, WGU1, 0, p.norm_ffn + DM)
;     TR_JOB_GU(p.ffn_w_up + (size_t)DM * DFF, WGU1, 128, p.norm_ffn + DM)
;     TR_JOB(p.cd_w_out, DM, DM, 0, DM, (bf16_t*)(ws + WS_WCD_OUT), 0, (const float*)nullptr)
;     const int mat = r / 32, rr = r % 32, kb_ = rr / 8, nb_ = rr % 8;
;     const float* W = (mat < 8 ? p.rg_w_x : p.rg_w_a) + (size_t)(mat & 7) * 65536;
;     return TrDesc{W + (size_t)(64 * kb_) * 256 + 32 * nb_, WRG + (size_t)mat * 65536 + (size_t)(32 * nb_) * 256 + 64 * kb_, nullptr, 256, 256};
; }
.Lcv_back_3:
.Lcv_job_cdi:
	s_load_dwordx2 s[60:61], s[24:25], 0x60
	s_load_dwordx2 s[62:63], s[24:25], 0xb8
	s_load_dwordx2 s[4:5], s[24:25], 0x8
	s_mov_b32 s6, 0xa000
	s_mov_b32 s7, 0x2000
	s_mov_b32 s75, 4
	s_and_b32 s9, s18, 63
	s_lshr_b32 s10, s18, 6
	s_add_i32 s10, s10, 2
	s_and_b32 s10, s10, 7
	s_sub_i32 s74, 79, s10
	s_lshr_b32 s74, s74, 3
	s_add_i32 s74, s74, 1
	s_lshl_b32 s11, s9, 6
	s_mul_i32 s11, s11, s6
	s_lshl_b32 s21, s10, 9
	s_add_u32 s11, s11, s21
	s_mul_i32 s23, s10, 128
	s_mul_i32 s23, s23, s7
	s_lshl_b32 s26, s9, 7
	s_add_u32 s23, s23, s26
	s_mov_b32 s70, 0x1000
	s_mov_b32 s71, 0
	s_mov_b32 s72, 0x800000
	s_mov_b32 s73, 0
	s_waitcnt lgkmcnt(0)
	s_add_u32 s60, s60, s11
	s_addc_u32 s61, s61, 0
	s_add_u32 s62, s62, 0x18300000
	s_addc_u32 s63, s63, 0
	s_add_u32 s62, s62, s23
	s_addc_u32 s63, s63, 0
	s_lshl_b32 s26, s7, 5
	s_add_u32 s64, s62, s26
	s_addc_u32 s65, s63, 0
	s_add_u32 s66, s64, s26
	s_addc_u32 s67, s65, 0
	s_add_u32 s68, s66, s26
	s_addc_u32 s69, s67, 0
	s_add_u32 s4, s4, 0x4000
	s_addc_u32 s5, s5, 0
	s_lshl_b32 s26, s9, 8
	s_add_u32 s4, s4, s26
	s_addc_u32 s5, s5, 0
	s_mov_b32 s8, 1
	s_branch .Lcv_run
.Lcv_back_4:
.Lcv_job_g1:
	s_load_dwordx2 s[60:61], s[24:25], 0x18
	s_load_dwordx2 s[62:63], s[24:25], 0xb8
	s_load_dwordx2 s[4:5], s[24:25], 0x10
	s_mov_b32 s6, 0xac00
	s_mov_b32 s7, 0x2000
	s_mov_b32 s75, 5
	s_and_b32 s9, s18, 63
	s_lshr_b32 s10, s18, 6
	s_add_i32 s10, s10, 3
	s_and_b32 s10, s10, 7
	s_sub_i32 s74, 85, s10
	s_lshr_b32 s74, s74, 3
	s_add_i32 s74, s74, 1
	s_lshl_b32 s11, s9, 6
	s_mul_i32 s11, s11, s6
	s_lshl_b32 s21, s10, 9
	s_add_u32 s11, s11, s21
	s_mul_i32 s23, s10, 256
	s_mul_i32 s23, s23, s7
	s_lshl_b32 s26, s9, 7
	s_add_u32 s23, s23, s26
	s_mov_b32 s70, 0x1000
	s_mov_b32 s71, 0
	s_mov_b32 s72, 0x1000000
	s_mov_b32 s73, 0
	s_waitcnt lgkmcnt(0)
	s_add_u32 s60, s60, 0xac00000
	s_addc_u32 s61, s61, 0
	s_add_u32 s60, s60, s11
	s_addc_u32 s61, s61, 0
	s_add_u32 s62, s62, 0x1f300000
	s_addc_u32 s63, s63, 0
	s_add_u32 s62, s62, s23
	s_addc_u32 s63, s63, 0
	s_lshl_b32 s26, s7, 5
	s_add_u32 s64, s62, s26
	s_addc_u32 s65, s63, 0
	s_add_u32 s66, s64, s26
	s_addc_u32 s67, s65, 0
	s_add_u32 s68, s66, s26
	s_addc_u32 s69, s67, 0
	s_add_u32 s4, s4, 0x4000
	s_addc_u32 s5, s5, 0
	s_lshl_b32 s26, s9, 8
	s_add_u32 s4, s4, s26
	s_addc_u32 s5, s5, 0
	s_mov_b32 s8, 1
	s_branch .Lcv_run
.Lcv_back_5:
.Lcv_job_rgx:
	s_load_dwordx2 s[60:61], s[24:25], 0x78
	s_load_dwordx2 s[62:63], s[24:25], 0xb8
	s_mov_b32 s6, 0x400
	s_mov_b32 s7, 0x200
	s_mov_b32 s75, 6
	s_sub_i32 s9, s18, 384
	s_cmp_lt_u32 s9, 64
	s_cselect_b32 s74, 1, 0
	s_and_b32 s9, s9, 63
	s_lshr_b32 s10, s9, 3
	s_bfe_u32 s21, s9, 0x20001
	s_and_b32 s26, s9, 1
	s_lshl_b32 s11, s10, 18
	s_lshl_b32 s27, s21, 16
	s_add_u32 s11, s11, s27
	s_lshl_b32 s27, s26, 9
	s_add_u32 s11, s11, s27
	s_lshl_b32 s23, s10, 17
	s_lshl_b32 s27, s26, 16
	s_add_u32 s23, s23, s27
	s_lshl_b32 s27, s21, 7
	s_add_u32 s23, s23, s27
	s_mov_b32 s70, 0
	s_mov_b32 s71, 0
	s_mov_b32 s72, 0
	s_mov_b32 s73, 0
	s_waitcnt lgkmcnt(0)
	s_add_u32 s60, s60, s11
	s_addc_u32 s61, s61, 0
	s_add_u32 s62, s62, 0x2f600000
	s_addc_u32 s63, s63, 0
	s_add_u32 s62, s62, s23
	s_addc_u32 s63, s63, 0
	s_lshl_b32 s26, s7, 5
	s_add_u32 s64, s62, s26
	s_addc_u32 s65, s63, 0
	s_add_u32 s66, s64, s26
	s_addc_u32 s67, s65, 0
	s_add_u32 s68, s66, s26
	s_addc_u32 s69, s67, 0
	s_mov_b32 s8, 0
	s_branch .Lcv_run
.Lcv_back_6:
.Lcv_job_rga:
	s_load_dwordx2 s[60:61], s[24:25], 0x88
	s_load_dwordx2 s[62:63], s[24:25], 0xb8
	s_mov_b32 s6, 0x400
	s_mov_b32 s7, 0x200
	s_mov_b32 s75, 7
	s_sub_i32 s9, s18, 448
	s_cmp_lt_u32 s9, 64
	s_cselect_b32 s74, 1, 0
	s_and_b32 s9, s9, 63
	s_lshr_b32 s10, s9, 3
	s_bfe_u32 s21, s9, 0x20001
	s_and_b32 s26, s9, 1
	s_lshl_b32 s11, s10, 18
	s_lshl_b32 s27, s21, 16
	s_add_u32 s11, s11, s27
	s_lshl_b32 s27, s26, 9
	s_add_u32 s11, s11, s27
	s_lshl_b32 s23, s10, 17
	s_lshl_b32 s27, s26, 16
	s_add_u32 s23, s23, s27
	s_lshl_b32 s27, s21, 7
	s_add_u32 s23, s23, s27
	s_mov_b32 s70, 0
	s_mov_b32 s71, 0
	s_mov_b32 s72, 0
	s_mov_b32 s73, 0
	s_waitcnt lgkmcnt(0)
	s_add_u32 s60, s60, s11
	s_addc_u32 s61, s61, 0
	s_add_u32 s62, s62, 0x2f700000
	s_addc_u32 s63, s63, 0
	s_add_u32 s62, s62, s23
	s_addc_u32 s63, s63, 0
	s_lshl_b32 s26, s7, 5
	s_add_u32 s64, s62, s26
	s_addc_u32 s65, s63, 0
	s_add_u32 s66, s64, s26
	s_addc_u32 s67, s65, 0
	s_add_u32 s68, s66, s26
	s_addc_u32 s69, s67, 0
	s_mov_b32 s8, 0
	s_branch .Lcv_run

; #define LAS __attribute__((address_space(3)))
; __device__ __forceinline__ void p0b_convert(const Params& p, LAS unsigned char* lds, int tw, int ntw, int wave, int lane) {
;     P0Item pi{&p, P0A_ITEMS}; tr_run(pi, tw, ntw, P0_NITEMS - P0A_ITEMS, (LAS float*)(lds + wave * 8704), lane);
; }
.Lcv_ret:
	s_cmp_eq_u32 s75, 0
	s_cbranch_scc1 .Lcv_back_0
	s_cmp_eq_u32 s75, 1
	s_cbranch_scc1 .Lcv_back_1
	s_cmp_eq_u32 s75, 2
	s_cbranch_scc1 .Lcv_back_2
	s_cmp_eq_u32 s75, 3
	s_cbranch_scc1 .Lcv_back_3
	s_cmp_eq_u32 s75, 4
	s_cbranch_scc1 .Lcv_back_4
	s_cmp_eq_u32 s75, 5
	s_cbranch_scc1 .Lcv_back_5
	s_cmp_eq_u32 s75, 6
	s_cbranch_scc1 .Lcv_back_6
	s_cmp_eq_u32 s75, 7
	s_cbranch_scc1 .Lcv_back_7
.Lcv_done:
	s_branch .LBB0_663

; template <int layer>
; __device__ __forceinline__ void layer_phases(const Params& p, LAS unsigned char* lds, const XcdBarrier& bar, int lo, int hi, int G, int gw, int ngw, int wave, int lane) {
;     ...
;                 if (G == 256) {
;                     if ((int)blockIdx.x < NG) { pg8::StaticOrder S; S.init(MTOK, AB_MAIN, NG, (int)blockIdx.x); pg8::gemm_phase<pg8::EpiBf16<true>, pg8::StaticOrder, true, true>(lds, g, S, E); }
;                     else p0b_convert(p, lds, ((int)blockIdx.x - NG) * NWAVES + wave, (G - NG) * NWAVES, wave, lane);
.LBB0_680:
.Lgs_entry:
	v_readlane_b32 s9, v240, 0
	s_cmp_gt_u32 s9, 0xbf
	s_cbranch_scc1 .Lgs_done
	v_readlane_b32 s24, v240, 2
	v_readlane_b32 s25, v240, 3
	s_load_dword s10, s[24:25], 0x0
	s_waitcnt lgkmcnt(0)
	s_cmpk_lg_i32 s10, 0x100
	s_cbranch_scc1 .Lgs_done
	s_mov_b64 exec, -1
	v_readlane_b32 s9, v240, 0
	v_readlane_b32 s10, v240, 1
	v_readlane_b32 s24, v240, 2
	v_readlane_b32 s25, v240, 3
	s_lshr_b32 s10, s10, 6
	s_lshl_b32 s9, s9, 3
	s_add_i32 s18, s9, s10
	s_sub_u32 s24, s24, 0xd0
	s_subb_u32 s25, s25, 0
	v_mbcnt_lo_u32_b32 v188, -1, 0
	v_mbcnt_hi_u32_b32 v188, -1, v188
	v_lshrrev_b32_e32 v3, 3, v188
	v_and_b32_e32 v132, 7, v188
	v_lshlrev_b32_e32 v186, 5, v3
.Lgs_job_u1:
	s_load_dwordx2 s[60:61], s[24:25], 0x20
	s_load_dwordx2 s[62:63], s[24:25], 0xb8
	s_load_dwordx2 s[4:5], s[24:25], 0x10
	s_mov_b32 s6, 0xac00
	s_mov_b32 s7, 0x2000
	s_mov_b32 s75, 0
	s_and_b32 s9, s18, 63
	s_lshr_b32 s10, s18, 6
	s_add_i32 s10, s10, 0
	s_cmp_ge_u32 s10, 24
	s_cselect_b32 s74, 24, 0
	s_sub_i32 s10, s10, s74
	s_sub_i32 s74, 85, s10
	s_mul_i32 s74, s74, 2731
	s_lshr_b32 s74, s74, 16
	s_add_i32 s74, s74, 1
	s_lshl_b32 s11, s9, 6
	s_mul_i32 s11, s11, s6
	s_lshl_b32 s21, s10, 9
	s_add_u32 s11, s11, s21
	s_mul_i32 s23, s10, 256
	s_add_i32 s23, s23, 128
	s_mul_i32 s23, s23, s7
	s_lshl_b32 s26, s9, 7
	s_add_u32 s23, s23, s26
	s_mov_b32 s70, 0x3000
	s_mov_b32 s71, 0
	s_mov_b32 s72, 0x3000000
	s_mov_b32 s73, 0
	s_waitcnt lgkmcnt(0)
	s_add_u32 s60, s60, 0xac00000
	s_addc_u32 s61, s61, 0
	s_add_u32 s60, s60, s11
	s_addc_u32 s61, s61, 0
	s_add_u32 s62, s62, 0x1f300000
	s_addc_u32 s63, s63, 0
	s_add_u32 s62, s62, s23
	s_addc_u32 s63, s63, 0
	s_lshl_b32 s26, s7, 5
	s_add_u32 s64, s62, s26
	s_addc_u32 s65, s63, 0
	s_add_u32 s66, s64, s26
	s_addc_u32 s67, s65, 0
	s_add_u32 s68, s66, s26
	s_addc_u32 s69, s67, 0
	s_add_u32 s4, s4, 0x4000
	s_addc_u32 s5, s5, 0
	s_lshl_b32 s26, s9, 8
	s_add_u32 s4, s4, s26
	s_addc_u32 s5, s5, 0
	s_mov_b32 s8, 1
	s_branch .Lgs_run
.Lgs_back_0:
.Lgs_job_cdo:
	s_load_dwordx2 s[60:61], s[24:25], 0xa0
	s_load_dwordx2 s[62:63], s[24:25], 0xb8
	s_mov_b32 s6, 0x4000
	s_mov_b32 s7, 0x2000
	s_mov_b32 s75, 1
	s_and_b32 s9, s18, 63
	s_lshr_b32 s10, s18, 6
	s_add_i32 s10, s10, 10
	s_cmp_ge_u32 s10, 24
	s_cselect_b32 s74, 24, 0
	s_sub_i32 s10, s10, s74
	s_sub_i32 s74, 31, s10
	s_mul_i32 s74, s74, 2731
	s_lshr_b32 s74, s74, 16
	s_add_i32 s74, s74, 1
	s_lshl_b32 s11, s9, 6
	s_mul_i32 s11, s11, s6
	s_lshl_b32 s21, s10, 9
	s_add_u32 s11, s11, s21
	s_mul_i32 s23, s10, 128
	s_mul_i32 s23, s23, s7
	s_lshl_b32 s26, s9, 7
	s_add_u32 s23, s23, s26
	s_mov_b32 s70, 0x3000
	s_mov_b32 s71, 0
	s_mov_b32 s72, 0x1800000
	s_mov_b32 s73, 0
	s_waitcnt lgkmcnt(0)
	s_add_u32 s60, s60, s11
	s_addc_u32 s61, s61, 0
	s_add_u32 s62, s62, 0x1d300000
	s_addc_u32 s63, s63, 0
	s_add_u32 s62, s62, s23
	s_addc_u32 s63, s63, 0
	s_lshl_b32 s26, s7, 5
	s_add_u32 s64, s62, s26
	s_addc_u32 s65, s63, 0
	s_add_u32 s66, s64, s26
	s_addc_u32 s67, s65, 0
	s_add_u32 s68, s66, s26
	s_addc_u32 s69, s67, 0
	s_mov_b32 s8, 0
	s_branch .Lgs_run

; __device__ __forceinline__ void xcd_barrier_complete(unsigned* bar, unsigned x, unsigned& nloc, unsigned& nx) {
;     const unsigned G = gridDim.x * gridDim.y * gridDim.z;
;     unsigned sum, cnt, mine, sp = 0u;
;     for (;;) {
;         sum = 0u; cnt = 0u; mine = 0u;
; #pragma unroll
;         for (unsigned j = 0; j < 16; ++j) { const unsigned c = xb_ld(&bar[XB_XCNT(j)]); sum += c; cnt += (c > 0u) ? 1u : 0u; mine = (j == x) ? c : mine; }
;         if (sum == G) break;
;         __builtin_amdgcn_s_sleep(1);
;         if ((++sp & 255u) == 0u) { if (xb_ld(&bar[XB_TMO])) break; if (sp > XB_SPIN_CAP) { atomicAdd(&bar[XB_TMO], 1u); break; } }
;     }
;     nloc = mine > 0u ? mine : 1u; nx = cnt > 0u ? cnt : 1u;
; }
; __device__ __forceinline__ void xcd_barrier(const XcdBarrier& b) {
;     asm volatile("s_waitcnt vmcnt(0)" ::: "memory");
;     __syncthreads();
;     if (threadIdx.x == 0) {
;         unsigned* bar = b.bar;
;         __builtin_amdgcn_s_waitcnt(0);
;         unsigned nloc = b.st[0], nx = b.st[1];
;         if (nloc == 0u) { xcd_barrier_complete(bar, b.x, nloc, nx); b.st[0] = nloc; b.st[1] = nx; }
; template <int layer>
; __device__ __forceinline__ void layer_phases(const Params& p, LAS unsigned char* lds, const XcdBarrier& bar, int lo, int hi, int G, int gw, int ngw, int wave, int lane) {
;     ...
;                 if (G == 256) {
;                     if ((int)blockIdx.x < NG) { pg8::StaticOrder S; S.init(MTOK, AB_MAIN, NG, (int)blockIdx.x); pg8::gemm_phase<pg8::EpiBf16<true>, pg8::StaticOrder, true, true>(lds, g, S, E); }
;                     else p0b_convert(p, lds, ((int)blockIdx.x - NG) * NWAVES + wave, (G - NG) * NWAVES, wave, lane);
;                 } else {
;                     p0b_convert(p, lds, gw, ngw, wave, lane); __syncthreads();
;                     pg8::StaticOrder S; S.init(MTOK, AB_MAIN, G, (int)blockIdx.x); pg8::gemm_phase<pg8::EpiBf16<true>, pg8::StaticOrder, true, true>(lds, g, S, E);
;                 }
;             } else {
;                 pg8::Gemm g{U, (const bf16_t*)(ws + WS_WCD_IN), MTOK, CD_IN, DM}; pg8::StaticOrder S; S.init(MTOK, CD_IN, G, (int)blockIdx.x);
;                 pg8::EpiBf16<true> E{PROJ, CD_IN, SSQ + 1 * MTOK};
;                 for (int rep = 0; rep < REP_GEMM; ++rep) { pg8::gemm_phase<pg8::EpiBf16<true>, pg8::StaticOrder, true, true>(lds, g, S, E); __syncthreads(); }
;             }
.Lgs_ret:
	s_cmp_eq_u32 s75, 0
	s_cbranch_scc1 .Lgs_back_0
	s_cmp_eq_u32 s75, 1
	s_cbranch_scc1 .Lgs_back_1
.Lgs_done:
	v_readlane_b32 s40, v240, 31
	v_readlane_b32 s41, v240, 32
	s_cmp_lt_i32 s41, 3
	v_readlane_b32 s42, v240, 33
	v_readlane_b32 s43, v240, 34
	s_cbranch_scc1 .LBB0_734
	s_waitcnt vmcnt(0)
	s_barrier
	s_mov_b64 s[0:1], exec
	v_readlane_b32 s2, v240, 23
	v_readlane_b32 s3, v240, 24
	s_and_b64 s[2:3], s[0:1], s[2:3]
	s_mov_b64 exec, s[2:3]
	s_cbranch_execz .LBB0_733
	s_add_i32 s2, 0, 0x20160
	s_waitcnt vmcnt(7)
	v_mov_b32_e32 v2, s2
	s_waitcnt vmcnt(0) expcnt(0) lgkmcnt(0)
	ds_read_b32 v4, v2
	s_add_i32 s2, 0, 0x20164
	v_mov_b32_e32 v2, s2
	ds_read_b32 v2, v2
	s_waitcnt lgkmcnt(1)
	v_cmp_ne_u32_e32 vcc, 0, v4
	s_cbranch_vccnz .LBB0_697
	v_readlane_b32 s2, v240, 2
	v_readlane_b32 s3, v240, 3
	s_load_dwordx2 s[6:7], s[2:3], 0x4
	v_readlane_b32 s8, v240, 20
	v_readlane_b32 s9, v240, 21
	s_add_u32 s2, s8, 0x1000
	s_addc_u32 s3, s9, 0
	s_add_u32 s4, s8, 0x1100
	s_addc_u32 s5, s9, 0
	s_waitcnt lgkmcnt(0)
	s_mul_i32 s16, s6, s92
	s_add_u32 s6, s8, 0x1200
	s_mul_i32 s16, s16, s7
	s_addc_u32 s7, s9, 0
	s_add_u32 s8, s8, 0x1300
	s_addc_u32 s9, s9, 0
	s_mov_b32 s17, 1
	v_mov_b32_e32 v18, 0
	s_branch .LBB0_685
